# combo13 + mixer post-pass row loop issues the loads of both halves (HGRN / GLA) of a row up front (one memory latency per row instead of two)
# baseline (speedup 1.0000x reference)
; __device__ __forceinline__ float sigmoidf_(float x) { return fast_rcp(1.0f + fast_exp2(-x * LOG2E)); }
; __device__ __forceinline__ void phase_post(const bf16* UB, const bf16* UC, bf16* Y, const float* hg  , const float* gg  , int r_0, int r_end, int r_step, int lane) {
;     ...
;             const bf16* po = UB + (size_t)r * 4096 + 2048 + 16 * lane; const bf16* pg = UB + (size_t)r * 4096 + 3072 + 16 * lane;
;             float v[16], g[16]; unpack16(*(const u32x4*)po, *(const u32x4*)(po + 8), v); unpack16(*(const u32x4*)pg, *(const u32x4*)(pg + 8), g);
;             float ss = 0.f;
; #pragma unroll
;             for (int e = 0; e < 16; ++e) { v[e] = v[e] * sigmoidf_(g[e]); ss += v[e] * v[e]; }
;             ss += __shfl_xor(ss, 1); ss += __shfl_xor(ss, 2); ss += __shfl_xor(ss, 4);
;             const float rstd = 1.0f / sqrtf(ss * (1.0f / 128.0f) + EPS);
;     ...
;             const bf16* po = UC + (size_t)r * 3584 + 1024 + 16 * lane; const bf16* pg = UC + (size_t)r * 3584 + 2048 + 16 * lane;
;             float v[16], g[16]; unpack16(*(const u32x4*)po, *(const u32x4*)(po + 8), v); unpack16(*(const u32x4*)pg, *(const u32x4*)(pg + 8), g);
.LBB0_515:
	v_lshl_add_u64 v[32:33], s[46:47], 0, v[168:169]
	s_mov_b64 s[10:11], 0x29801000
	v_lshl_add_u64 v[50:51], v[32:33], 0, s[10:11]
	s_mov_b64 s[10:11], 0x29801800
	v_lshl_add_u64 v[54:55], v[32:33], 0, s[10:11]
	v_add_co_u32_e32 v32, vcc, 0x29801000, v32
	global_load_dwordx4 v[50:53], v[50:51], off offset:16
	s_nop 0
	global_load_dwordx4 v[54:57], v[54:55], off offset:16
	v_addc_co_u32_e32 v33, vcc, 0, v33, vcc
	global_load_dwordx4 v[58:61], v[32:33], off
	global_load_dwordx4 v[62:65], v[32:33], off offset:2048
	v_lshl_add_u64 v[34:35], s[44:45], 0, v[168:169]
	s_mov_b32 s1, 0x44800000
	v_add_co_u32_e64 v36, s[42:43], s1, v34
	v_lshl_add_u64 v[44:45], s[36:37], 0, v[168:169]
	s_nop 0
	v_addc_co_u32_e64 v37, s[42:43], 0, v35, s[42:43]
	s_mov_b64 s[10:11], 0x31800800
	v_add_co_u32_e64 v40, s[42:43], s63, v44
	v_lshl_add_u64 v[38:39], v[44:45], 0, s[10:11]
	s_mov_b64 s[10:11], 0x31801000
	v_addc_co_u32_e64 v41, s[42:43], 0, v45, s[42:43]
	s_mov_b32 s1, 0x31801000
	v_lshl_add_u64 v[42:43], v[44:45], 0, s[10:11]
	v_add_co_u32_e64 v44, s[42:43], s1, v44
	s_mov_b32 s1, 0x44801000
	s_nop 0
	v_addc_co_u32_e64 v45, s[42:43], 0, v45, s[42:43]
	global_load_dwordx4 v[108:111], v[38:39], off offset:16
	global_load_dwordx4 v[122:125], v[42:43], off offset:16
	global_load_dwordx4 v[114:117], v[44:45], off
	global_load_dwordx4 v[126:129], v[40:41], off offset:2048
	v_add_co_u32_e64 v34, s[42:43], s1, v34
	s_add_i32 s12, s12, 8
	s_nop 0
	v_addc_co_u32_e64 v35, s[42:43], 0, v35, s[42:43]
	s_add_u32 s36, s36, 0xe000
	s_addc_u32 s37, s37, 0
	s_add_u32 s44, s44, 0xc000
	s_addc_u32 s45, s45, 0
	s_add_u32 s46, s46, 0x10000
	s_addc_u32 s47, s47, 0
	s_cmp_ge_i32 s12, s0
	s_waitcnt vmcnt(7)
	v_lshlrev_b32_e32 v66, 16, v50
	s_waitcnt vmcnt(6)
	v_lshlrev_b32_e32 v71, 16, v56
	v_and_b32_e32 v56, 0xffff0000, v56
	v_and_b32_e32 v67, 0xffff0000, v50
	s_waitcnt vmcnt(4)
	v_lshlrev_b32_e32 v76, 16, v62
	v_and_b32_e32 v62, 0xffff0000, v62
	v_lshlrev_b32_e32 v50, 16, v54
	v_lshlrev_b32_e32 v72, 16, v57
	v_and_b32_e32 v57, 0xffff0000, v57
	v_lshlrev_b32_e32 v77, 16, v63
	v_and_b32_e32 v63, 0xffff0000, v63
	v_mul_f32_e32 v56, 0xbfb8aa3b, v56
	v_mul_f32_e32 v62, 0xbfb8aa3b, v62
	v_lshlrev_b32_e32 v68, 16, v51
	v_and_b32_e32 v69, 0xffff0000, v51
	v_and_b32_e32 v51, 0xffff0000, v54
	v_mul_f32_e32 v50, 0xbfb8aa3b, v50
	v_mul_f32_e32 v57, 0xbfb8aa3b, v57
	v_mul_f32_e32 v76, 0xbfb8aa3b, v76
	v_mul_f32_e32 v63, 0xbfb8aa3b, v63
	v_exp_f32_e32 v56, v56
	v_exp_f32_e32 v62, v62
	v_mul_f32_e32 v51, 0xbfb8aa3b, v51
	v_mul_f32_e32 v72, 0xbfb8aa3b, v72
	v_mul_f32_e32 v77, 0xbfb8aa3b, v77
	v_exp_f32_e32 v50, v50
	v_exp_f32_e32 v57, v57
	v_exp_f32_e32 v76, v76
	v_exp_f32_e32 v63, v63
	v_lshlrev_b32_e32 v78, 16, v64
	v_exp_f32_e32 v51, v51
	v_exp_f32_e32 v72, v72
	v_exp_f32_e32 v77, v77
	v_and_b32_e32 v64, 0xffff0000, v64
	v_mul_f32_e32 v78, 0xbfb8aa3b, v78
	v_lshlrev_b32_e32 v79, 16, v65
	v_mul_f32_e32 v64, 0xbfb8aa3b, v64
	v_exp_f32_e32 v78, v78
	v_add_f32_e32 v56, 1.0, v56
	v_add_f32_e32 v62, 1.0, v62
	v_and_b32_e32 v65, 0xffff0000, v65
	v_mul_f32_e32 v79, 0xbfb8aa3b, v79
	v_exp_f32_e32 v64, v64
	v_add_f32_e32 v50, 1.0, v50
	v_add_f32_e32 v57, 1.0, v57
	v_add_f32_e32 v76, 1.0, v76
	v_add_f32_e32 v63, 1.0, v63
	v_rcp_f32_e32 v56, v56
	v_rcp_f32_e32 v62, v62
	v_mul_f32_e32 v65, 0xbfb8aa3b, v65
	v_exp_f32_e32 v79, v79
	v_add_f32_e32 v51, 1.0, v51
	v_add_f32_e32 v72, 1.0, v72
	v_add_f32_e32 v77, 1.0, v77
	v_rcp_f32_e32 v80, v50
	v_rcp_f32_e32 v50, v57
	v_rcp_f32_e32 v57, v76
	v_rcp_f32_e32 v63, v63
	v_exp_f32_e32 v65, v65
	v_rcp_f32_e32 v81, v51
	v_rcp_f32_e32 v51, v72
	v_rcp_f32_e32 v72, v77
	v_lshlrev_b32_e32 v70, 16, v52
	v_and_b32_e32 v52, 0xffff0000, v52
	v_lshlrev_b32_e32 v54, 16, v55
	v_and_b32_e32 v32, 0xffff0000, v53
	v_lshlrev_b32_e32 v33, 16, v53
	v_lshlrev_b32_e32 v53, 16, v58
	v_and_b32_e32 v58, 0xffff0000, v58
	v_add_f32_e32 v78, 1.0, v78
	v_and_b32_e32 v55, 0xffff0000, v55
	v_lshlrev_b32_e32 v73, 16, v59
	v_and_b32_e32 v59, 0xffff0000, v59
	v_mul_f32_e32 v54, 0xbfb8aa3b, v54
	v_add_f32_e32 v64, 1.0, v64
	v_rcp_f32_e32 v76, v78
	v_mul_f32_e32 v52, v56, v52
	v_mul_f32_e32 v56, v62, v58
	v_mul_f32_e32 v55, 0xbfb8aa3b, v55
	v_exp_f32_e32 v54, v54
	v_add_f32_e32 v79, 1.0, v79
	v_rcp_f32_e32 v64, v64
	v_mul_f32_e32 v53, v57, v53
	v_mul_f32_e32 v58, v63, v59
	v_mul_f32_e32 v63, v56, v56
	v_mul_f32_e32 v71, 0xbfb8aa3b, v71
	v_exp_f32_e32 v55, v55
	v_add_f32_e32 v65, 1.0, v65
	v_rcp_f32_e32 v77, v79
	v_mul_f32_e32 v57, v72, v73
	v_fmac_f32_e32 v63, v53, v53
	v_lshlrev_b32_e32 v74, 16, v60
	v_exp_f32_e32 v71, v71
	v_rcp_f32_e32 v65, v65
	v_fmac_f32_e32 v63, v57, v57
	v_and_b32_e32 v60, 0xffff0000, v60
	v_mul_f32_e32 v59, v76, v74
	v_fmac_f32_e32 v63, v58, v58
	v_lshlrev_b32_e32 v75, 16, v61
	v_add_f32_e32 v54, 1.0, v54
	v_mul_f32_e32 v60, v64, v60
	v_fmac_f32_e32 v63, v59, v59
	v_and_b32_e32 v61, 0xffff0000, v61
	v_add_f32_e32 v55, 1.0, v55
	v_rcp_f32_e32 v54, v54
	v_mul_f32_e32 v62, v77, v75
	v_fmac_f32_e32 v63, v60, v60
	v_add_f32_e32 v71, 1.0, v71
	v_rcp_f32_e32 v55, v55
	v_mul_f32_e32 v61, v65, v61
	v_fmac_f32_e32 v63, v62, v62
	v_rcp_f32_e32 v71, v71
	v_mul_f32_e32 v66, v80, v66
	v_fmac_f32_e32 v63, v61, v61
	v_mul_f32_e32 v67, v81, v67
	v_fmac_f32_e32 v63, v66, v66
	v_mul_f32_e32 v54, v54, v68
	v_fmac_f32_e32 v63, v67, v67
	v_mul_f32_e32 v55, v55, v69
	v_fmac_f32_e32 v63, v54, v54
	v_mul_f32_e32 v68, v71, v70
	v_fmac_f32_e32 v63, v55, v55
	v_pk_mul_f32 v[32:33], v[50:51], v[32:33]
	v_fmac_f32_e32 v63, v68, v68
	v_pk_mul_f32 v[50:51], v[32:33], v[32:33]
	v_fmac_f32_e32 v63, v52, v52
	v_add_f32_e32 v51, v51, v63
	v_add_f32_e32 v50, v50, v51
	ds_bpermute_b32 v51, v46, v50
	s_waitcnt lgkmcnt(0)
; __device__ __forceinline__ void phase_post(const bf16* UB, const bf16* UC, bf16* Y, const float* hg  , const float* gg  , int r_0, int r_end, int r_step, int lane) {
;     ...
;             const float rstd = 1.0f / sqrtf(ss * (1.0f / 128.0f) + EPS);
; #pragma unroll
;             for (int e = 0; e < 16; ++e) v[e] = v[e] * rstd * g1[e];
;             u32x4 oa, ob; pack16(v, oa, ob);
;             bf16* py = Y + (size_t)r * 3072 + 1024 + 16 * lane; *(u32x4*)py = oa; *(u32x4*)(py + 8) = ob;
;         }
;         {
;             const bf16* po = UC + (size_t)r * 3584 + 1024 + 16 * lane; const bf16* pg = UC + (size_t)r * 3584 + 2048 + 16 * lane;
;             float v[16], g[16]; unpack16(*(const u32x4*)po, *(const u32x4*)(po + 8), v); unpack16(*(const u32x4*)pg, *(const u32x4*)(pg + 8), g);
;             float ss = 0.f;
; #pragma unroll
;             for (int e = 0; e < 16; ++e) ss += v[e] * v[e];
;             ss += __shfl_xor(ss, 1); ss += __shfl_xor(ss, 2); ss += __shfl_xor(ss, 4); ss += __shfl_xor(ss, 8);
	v_add_f32_e32 v50, v50, v51
	ds_bpermute_b32 v51, v47, v50
	s_waitcnt lgkmcnt(0)
	v_add_f32_e32 v50, v50, v51
	ds_bpermute_b32 v51, v48, v50
	s_waitcnt lgkmcnt(0)
	v_add_f32_e32 v50, v50, v51
	v_fmamk_f32 v50, v50, 0x3c000000, v223
	v_mul_f32_e32 v51, 0x4f800000, v50
	v_cmp_gt_f32_e32 vcc, s62, v50
	s_nop 1
	v_cndmask_b32_e32 v50, v50, v51, vcc
	v_sqrt_f32_e32 v51, v50
	s_nop 0
	v_add_u32_e32 v63, -1, v51
	v_add_u32_e32 v64, 1, v51
	v_fma_f32 v65, -v63, v51, v50
	v_fma_f32 v69, -v64, v51, v50
	v_cmp_ge_f32_e64 s[42:43], 0, v65
	s_nop 1
	v_cndmask_b32_e64 v51, v51, v63, s[42:43]
	v_cmp_lt_f32_e64 s[42:43], 0, v69
	s_nop 1
	v_cndmask_b32_e64 v51, v51, v64, s[42:43]
	v_mul_f32_e32 v63, 0x37800000, v51
	v_cndmask_b32_e32 v51, v51, v63, vcc
	v_cmp_class_f32_e32 vcc, v50, v224
	s_nop 1
	v_cndmask_b32_e32 v50, v51, v50, vcc
	v_div_scale_f32 v51, s[10:11], v50, v50, 1.0
	v_rcp_f32_e32 v64, v51
	v_div_scale_f32 v63, vcc, 1.0, v50, 1.0
	v_fma_f32 v65, -v51, v64, 1.0
	v_fmac_f32_e32 v64, v65, v64
	v_mul_f32_e32 v65, v63, v64
	v_fma_f32 v69, -v51, v65, v63
	v_fmac_f32_e32 v65, v69, v64
	v_fma_f32 v51, -v51, v65, v63
	v_div_fmas_f32 v51, v51, v64, v65
	v_div_fixup_f32 v50, v51, v50, 1.0
	v_mul_f32_e32 v51, v53, v50
	v_mul_f32_e32 v53, v56, v50
	v_mul_f32_e32 v56, v57, v50
	v_mul_f32_e32 v57, v58, v50
	v_mul_f32_e32 v58, v59, v50
	v_mul_f32_e32 v59, v60, v50
	v_mul_f32_e32 v60, v62, v50
	v_mul_f32_e32 v61, v61, v50
	v_mul_f32_e32 v62, v66, v50
	v_mul_f32_e32 v63, v67, v50
	v_mul_f32_e32 v54, v54, v50
	v_mul_f32_e32 v55, v55, v50
	v_mul_f32_e32 v64, v68, v50
	v_mul_f32_e32 v52, v52, v50
	v_mul_f32_e32 v33, v33, v50
	v_mul_f32_e32 v32, v32, v50
	v_mul_f32_e32 v50, v0, v51
	v_mul_f32_e32 v51, v1, v53
	v_mul_f32_e32 v53, v2, v56
	v_mul_f32_e32 v56, v3, v57
	v_mul_f32_e32 v57, v4, v58
	v_mul_f32_e32 v58, v5, v59
	v_mul_f32_e32 v59, v6, v60
	v_mul_f32_e32 v60, v7, v61
	v_mul_f32_e32 v55, v11, v55
	v_mul_f32_e32 v65, v13, v52
	v_cvt_pk_bf16_f32 v50, v50, v51
	v_cvt_pk_bf16_f32 v51, v53, v56
	v_cvt_pk_bf16_f32 v52, v57, v58
	v_cvt_pk_bf16_f32 v53, v59, v60
	v_mul_f32_e32 v61, v8, v62
	v_mul_f32_e32 v62, v9, v63
	v_mul_f32_e32 v63, v10, v54
	v_mul_f32_e32 v64, v12, v64
	v_mul_f32_e32 v33, v14, v33
	v_mul_f32_e32 v32, v15, v32
	v_cvt_pk_bf16_f32 v54, v61, v62
	v_cvt_pk_bf16_f32 v55, v63, v55
	v_cvt_pk_bf16_f32 v56, v64, v65
	v_cvt_pk_bf16_f32 v57, v33, v32
	global_store_dwordx4 v[36:37], v[50:53], off offset:2048
	global_store_dwordx4 v[36:37], v[54:57], off offset:2064
	s_waitcnt vmcnt(5)
	v_and_b32_e32 v61, 0xffff0000, v109
	s_waitcnt vmcnt(4)
	v_lshlrev_b32_e32 v32, 16, v125
	v_and_b32_e32 v112, 0xffff0000, v125
	s_waitcnt vmcnt(2)
	v_lshlrev_b32_e32 v71, 16, v126
	v_lshlrev_b32_e32 v125, 16, v109
	v_lshlrev_b32_e32 v62, 16, v122
	v_lshlrev_b32_e32 v63, 16, v108
	v_and_b32_e32 v109, 0xffff0000, v108
	v_and_b32_e32 v108, 0xffff0000, v122
	v_lshlrev_b32_e32 v122, 16, v117
	v_and_b32_e32 v64, 0xffff0000, v117
	v_lshlrev_b32_e32 v67, 16, v128
	v_and_b32_e32 v117, 0xffff0000, v128
	v_lshlrev_b32_e32 v128, 16, v115
	v_and_b32_e32 v68, 0xffff0000, v115
	v_and_b32_e32 v115, 0xffff0000, v126
	v_mul_f32_e32 v89, v71, v71
	v_lshlrev_b32_e32 v33, 16, v111
	v_and_b32_e32 v113, 0xffff0000, v111
	v_lshlrev_b32_e32 v59, 16, v110
	v_lshlrev_b32_e32 v58, 16, v124
	v_and_b32_e32 v111, 0xffff0000, v110
	v_and_b32_e32 v110, 0xffff0000, v124
	v_lshlrev_b32_e32 v124, 16, v123
	v_and_b32_e32 v60, 0xffff0000, v123
	v_lshlrev_b32_e32 v123, 16, v129
	v_and_b32_e32 v65, 0xffff0000, v129
	v_lshlrev_b32_e32 v129, 16, v127
	v_fmac_f32_e32 v89, v115, v115
	v_and_b32_e32 v69, 0xffff0000, v127
	v_fmac_f32_e32 v89, v129, v129
	v_fmac_f32_e32 v89, v69, v69
	v_fmac_f32_e32 v89, v67, v67
	v_fmac_f32_e32 v89, v117, v117
	v_fmac_f32_e32 v89, v123, v123
	v_fmac_f32_e32 v89, v65, v65
	v_fmac_f32_e32 v89, v63, v63
	v_fmac_f32_e32 v89, v109, v109
	v_mov_b32_e32 v72, v111
	v_mov_b32_e32 v73, v59
	v_fmac_f32_e32 v89, v125, v125
	v_pk_mul_f32 v[72:73], v[72:73], v[72:73]
	v_fmac_f32_e32 v89, v61, v61
	v_mov_b32_e32 v126, v113
	v_mov_b32_e32 v127, v33
	v_add_f32_e32 v73, v73, v89
	v_pk_mul_f32 v[126:127], v[126:127], v[126:127]
	v_add_f32_e32 v72, v72, v73
	v_add_f32_e32 v127, v127, v72
	v_add_f32_e32 v126, v126, v127
	ds_bpermute_b32 v127, v46, v126
	v_mul_f32_e32 v75, 0xbfb8aa3b, v58
	v_mul_f32_e32 v76, 0xbfb8aa3b, v110
	v_mul_f32_e32 v77, 0xbfb8aa3b, v124
	v_exp_f32_e32 v75, v75
	s_waitcnt lgkmcnt(0)
	v_add_f32_e32 v126, v126, v127
	ds_bpermute_b32 v127, v47, v126
	v_mul_f32_e32 v80, 0xbfb8aa3b, v108
	v_exp_f32_e32 v76, v76
	v_exp_f32_e32 v77, v77
	v_exp_f32_e32 v80, v80
	s_waitcnt lgkmcnt(0)
	v_add_f32_e32 v126, v126, v127
	ds_bpermute_b32 v127, v48, v126
	v_add_f32_e32 v75, 1.0, v75
	v_add_f32_e32 v91, 1.0, v76
	v_add_f32_e32 v77, 1.0, v77
	v_rcp_f32_e32 v76, v75
	s_waitcnt lgkmcnt(0)
	v_add_f32_e32 v126, v126, v127
	ds_bpermute_b32 v127, v49, v126
	v_add_f32_e32 v93, 1.0, v80
	v_rcp_f32_e32 v80, v77
	v_lshlrev_b32_e32 v70, 16, v114
	v_mul_f32_e32 v87, 0xbfb8aa3b, v70
	s_waitcnt lgkmcnt(0)
; __device__ __forceinline__ float siluf_(float x) { return x * sigmoidf_(x); }
; __device__ __forceinline__ void phase_post(const bf16* UB, const bf16* UC, bf16* Y, const float* hg  , const float* gg  , int r_0, int r_end, int r_step, int lane) {
;     ...
;             ss += __shfl_xor(ss, 1); ss += __shfl_xor(ss, 2); ss += __shfl_xor(ss, 4); ss += __shfl_xor(ss, 8);
;             const float rstd = 1.0f / sqrtf(ss * (1.0f / 256.0f) + EPS);
; #pragma unroll
;             for (int e = 0; e < 16; ++e) v[e] = v[e] * rstd * g2[e] * siluf_(g[e]);
;             u32x4 oa, ob; pack16(v, oa, ob);
;             bf16* py = Y + (size_t)r * 3072 + 2048 + 16 * lane; *(u32x4*)py = oa; *(u32x4*)(py + 8) = ob;
	v_add_f32_e32 v126, v126, v127
	v_fmamk_f32 v126, v126, 0x3b800000, v223
	v_mul_f32_e32 v127, 0x4f800000, v126
	v_cmp_gt_f32_e32 vcc, s62, v126
	v_exp_f32_e32 v87, v87
	v_lshlrev_b32_e32 v66, 16, v116
	v_cndmask_b32_e32 v126, v126, v127, vcc
	v_sqrt_f32_e32 v127, v126
	v_and_b32_e32 v116, 0xffff0000, v116
	v_and_b32_e32 v114, 0xffff0000, v114
	v_mul_f32_e32 v74, 0xbfb8aa3b, v32
	v_add_u32_e32 v72, -1, v127
	v_add_u32_e32 v73, 1, v127
	v_fma_f32 v75, -v72, v127, v126
	v_fma_f32 v77, -v73, v127, v126
	v_cmp_ge_f32_e64 s[42:43], 0, v75
	v_mul_f32_e32 v78, 0xbfb8aa3b, v60
	v_mul_f32_e32 v81, 0xbfb8aa3b, v122
	v_cndmask_b32_e64 v127, v127, v72, s[42:43]
	v_cmp_lt_f32_e64 s[42:43], 0, v77
	v_mul_f32_e32 v82, 0xbfb8aa3b, v64
	v_mul_f32_e32 v83, 0xbfb8aa3b, v66
	v_cndmask_b32_e64 v127, v127, v73, s[42:43]
	v_mul_f32_e32 v72, 0x37800000, v127
	v_cndmask_b32_e32 v127, v127, v72, vcc
	v_cmp_class_f32_e32 vcc, v126, v224
	v_mul_f32_e32 v84, 0xbfb8aa3b, v116
	v_mul_f32_e32 v85, 0xbfb8aa3b, v128
	v_cndmask_b32_e32 v126, v127, v126, vcc
	v_div_scale_f32 v127, s[10:11], v126, v126, 1.0
	v_rcp_f32_e32 v73, v127
	v_mul_f32_e32 v86, 0xbfb8aa3b, v68
	v_mul_f32_e32 v88, 0xbfb8aa3b, v114
	v_exp_f32_e32 v74, v74
	v_fma_f32 v75, -v127, v73, 1.0
	v_exp_f32_e32 v78, v78
	v_div_scale_f32 v72, vcc, 1.0, v126, 1.0
	v_fmac_f32_e32 v73, v75, v73
	v_mul_f32_e32 v79, 0xbfb8aa3b, v62
	v_mul_f32_e32 v90, 0xbfb8aa3b, v112
	v_exp_f32_e32 v81, v81
	v_exp_f32_e32 v82, v82
	v_exp_f32_e32 v83, v83
	v_exp_f32_e32 v84, v84
	v_exp_f32_e32 v85, v85
	v_exp_f32_e32 v86, v86
	v_exp_f32_e32 v88, v88
	v_mul_f32_e32 v75, v72, v73
	v_exp_f32_e32 v79, v79
	v_exp_f32_e32 v90, v90
	v_add_f32_e32 v87, 1.0, v87
	v_fma_f32 v77, -v127, v75, v72
	v_rcp_f32_e32 v100, v87
	v_fmac_f32_e32 v75, v77, v73
	v_add_f32_e32 v74, 1.0, v74
	v_add_f32_e32 v92, 1.0, v78
	v_fma_f32 v127, -v127, v75, v72
	v_add_f32_e32 v81, 1.0, v81
	v_add_f32_e32 v94, 1.0, v82
	v_add_f32_e32 v83, 1.0, v83
	v_add_f32_e32 v95, 1.0, v84
	v_add_f32_e32 v85, 1.0, v85
	v_add_f32_e32 v97, 1.0, v86
	v_add_f32_e32 v99, 1.0, v88
	v_rcp_f32_e32 v74, v74
	v_rcp_f32_e32 v82, v92
	v_div_fmas_f32 v127, v127, v73, v75
	v_add_f32_e32 v79, 1.0, v79
	v_add_f32_e32 v104, 1.0, v90
	v_rcp_f32_e32 v78, v91
	v_rcp_f32_e32 v86, v93
	v_rcp_f32_e32 v88, v81
	v_rcp_f32_e32 v90, v94
	v_rcp_f32_e32 v92, v83
	v_rcp_f32_e32 v94, v95
	v_rcp_f32_e32 v96, v85
	v_rcp_f32_e32 v98, v97
	v_rcp_f32_e32 v102, v99
	v_div_fixup_f32 v101, v127, v126, 1.0
	v_rcp_f32_e32 v84, v79
	v_pk_mul_f32 v[126:127], v[100:101], v[70:71]
	v_rcp_f32_e32 v100, v104
	v_mov_b32_e32 v81, v101
	v_mov_b32_e32 v83, v101
	v_mov_b32_e32 v75, v101
	v_mov_b32_e32 v103, v101
	v_mov_b32_e32 v97, v101
	v_mov_b32_e32 v99, v101
	v_mov_b32_e32 v93, v101
	v_mov_b32_e32 v95, v101
	v_mov_b32_e32 v89, v101
	v_mov_b32_e32 v91, v101
	v_mov_b32_e32 v87, v101
	v_mov_b32_e32 v77, v101
	v_mov_b32_e32 v79, v101
	v_pk_mul_f32 v[124:125], v[80:81], v[124:125]
	v_pk_mul_f32 v[60:61], v[82:83], v[60:61]
	v_pk_mul_f32 v[32:33], v[74:75], v[32:33]
	v_mov_b32_e32 v85, v101
	v_mul_f32_e32 v127, v16, v127
	v_pk_mul_f32 v[114:115], v[102:103], v[114:115]
	v_pk_mul_f32 v[128:129], v[96:97], v[128:129]
	v_pk_mul_f32 v[68:69], v[98:99], v[68:69]
	v_pk_mul_f32 v[66:67], v[92:93], v[66:67]
	v_pk_mul_f32 v[116:117], v[94:95], v[116:117]
	v_pk_mul_f32 v[122:123], v[88:89], v[122:123]
	v_pk_mul_f32 v[64:65], v[90:91], v[64:65]
	v_pk_mul_f32 v[108:109], v[86:87], v[108:109]
	v_pk_mul_f32 v[58:59], v[76:77], v[58:59]
	v_pk_mul_f32 v[110:111], v[78:79], v[110:111]
	v_mul_f32_e32 v125, v26, v125
	v_mul_f32_e32 v61, v27, v61
	v_mul_f32_e32 v33, v30, v33
	v_pk_mul_f32 v[62:63], v[84:85], v[62:63]
	v_mul_f32_e32 v126, v126, v127
	v_mul_f32_e32 v115, v17, v115
	v_mul_f32_e32 v127, v18, v129
	v_mul_f32_e32 v129, v19, v69
	v_mul_f32_e32 v67, v20, v67
	v_mul_f32_e32 v117, v21, v117
	v_mul_f32_e32 v123, v22, v123
	v_mul_f32_e32 v65, v23, v65
	v_mul_f32_e32 v109, v25, v109
	v_mul_f32_e32 v59, v28, v59
	v_mul_f32_e32 v111, v29, v111
	v_mul_f32_e32 v124, v124, v125
	v_mul_f32_e32 v125, v60, v61
	v_mul_f32_e32 v60, v32, v33
	v_pk_mul_f32 v[32:33], v[100:101], v[112:113]
	v_mul_f32_e32 v63, v24, v63
	v_mul_f32_e32 v114, v114, v115
	v_mul_f32_e32 v115, v128, v127
	v_mul_f32_e32 v127, v68, v129
	v_mul_f32_e32 v128, v66, v67
	v_mul_f32_e32 v116, v116, v117
	v_mul_f32_e32 v117, v122, v123
	v_mul_f32_e32 v122, v64, v65
	v_mul_f32_e32 v129, v108, v109
	v_mul_f32_e32 v58, v58, v59
	v_mul_f32_e32 v59, v110, v111
	v_cvt_pk_bf16_f32 v108, v126, v114
	v_cvt_pk_bf16_f32 v109, v115, v127
	v_cvt_pk_bf16_f32 v110, v128, v116
	v_cvt_pk_bf16_f32 v111, v117, v122
	v_mul_f32_e32 v33, v31, v33
	v_mul_f32_e32 v123, v62, v63
	v_cvt_pk_bf16_f32 v112, v123, v129
	v_cvt_pk_bf16_f32 v113, v124, v125
	v_cvt_pk_bf16_f32 v114, v58, v59
	v_mul_f32_e32 v32, v32, v33
	v_cvt_pk_bf16_f32 v115, v60, v32
	global_store_dwordx4 v[34:35], v[108:111], off
	global_store_dwordx4 v[34:35], v[112:115], off offset:16
	s_cbranch_scc0 .LBB0_515
